# ssm_p3 scan: the bf16 conversions and the LDS state writes are issued as two bursts after the 128 scan FMAs instead of interleaved with them
# baseline (speedup 1.0000x reference)
; __device__ __forceinline__ unsigned pk2(float lo, float hi) { const f32x2 v = {lo, hi}; return __builtin_bit_cast(unsigned, __builtin_convertvector(v, bf16x2_t)); }
; __device__ __forceinline__ float bflo(unsigned w) { return __uint_as_float(w << 16); }
; __device__ __forceinline__ float bfhi(unsigned w) { return __uint_as_float(w & 0xffff0000u); }
; #define LDS_FENCE() asm volatile("s_waitcnt lgkmcnt(0)" ::: "memory")
; template <bool BWD, int MODE  >
; __device__ __forceinline__ void ssm_pass(const bf16* proj, int rowbase, int g, const bf16x8* BBp, const bf16x8* CCp, float ar, float ai, float& sr, float& si,
;                                          LAS unsigned* XS, int lane, f32x4* ysc, const float* Dp, bf16* zbuf) {
;     ...
;     for (int c = 0; c < 16; ++c) {
;         const int ch = BWD ? 15 - c : c;
;         bf16x8 unext = ucur;
;         if (c < 15) unext = *(const bf16x8*)(up + (size_t)(BWD ? ch - 1 : ch + 1) * 32 * DIN);
;         f32x4 y0 = (f32x4){0.f, 0.f, 0.f, 0.f}, y1 = y0; bf16 uvl[8];
;         if (MODE == 2) {
;             y0 = ysc[(ch * 2 + 0) * 64 + lane]; y1 = ysc[(ch * 2 + 1) * 64 + lane];
; #pragma unroll
;             for (int q = 0; q < 8; ++q) uvl[q] = proj[(size_t)(rowbase + 32 * ch + 16 * (q >> 2) + 4 * (lane >> 4) + (q & 3)) * DIN + 768 + g * 16 + (lane & 15)];
;         }
;         f32x16 z16;
; #pragma unroll
;         for (int r = 0; r < 16; ++r) z16[r] = 0.f;
;         const f32x16 x0 = __builtin_amdgcn_mfma_f32_32x32x16_bf16(ucur, bb[0], z16, 0, 0, 0);
;         const f32x16 x1 = __builtin_amdgcn_mfma_f32_32x32x16_bf16(ucur, bb[1], z16, 0, 0, 0);
;         const f32x16 x2 = __builtin_amdgcn_mfma_f32_32x32x16_bf16(ucur, bb[2], z16, 0, 0, 0);
;         const f32x16 x3 = __builtin_amdgcn_mfma_f32_32x32x16_bf16(ucur, bb[3], z16, 0, 0, 0);
; #pragma unroll
;         for (int r = 0; r < 16; ++r) { const int t = crow(r, hi); XS[t * XS_STRIDE + ql] = pk2(x0[r], x2[r]); XS[t * XS_STRIDE + 32 + ql] = pk2(x1[r], x3[r]); }
;         LDS_FENCE();
; #pragma unroll
;         for (int tt = 0; tt < 32; ++tt) {
;             const int t = BWD ? 31 - tt : tt;
;             const unsigned v = XS[t * XS_STRIDE + lane];
;             const float nr = fmaf(ar, sr, fmaf(-ai, si, bflo(v))), ni = fmaf(ar, si, fmaf(ai, sr, bfhi(v)));
;             sr = nr; si = ni;
;             if (MODE > 0) XS[t * XS_STRIDE + lane] = pk2(sr, si);
.Lp3n_loopa:
	v_add_u32_e32 v156, v157, v156
	s_mov_b64 exec, s[60:61]
	global_load_dwordx4 v[138:141], v156, s[6:7]
	s_mov_b64 exec, s[62:63]
	global_load_dwordx4 v[142:145], v156, s[6:7]
	s_mov_b64 exec, -1
	v_mfma_f32_32x32x16_bf16 v[2:17], v[130:133], v[66:69], 0
	v_mfma_f32_32x32x16_bf16 v[18:33], v[130:133], v[70:73], 0
	v_mfma_f32_32x32x16_bf16 v[34:49], v[130:133], v[74:77], 0
	v_mfma_f32_32x32x16_bf16 v[50:65], v[130:133], v[78:81], 0
	v_mfma_f32_32x32x16_bf16 v[2:17], v[134:137], v[82:85], v[2:17]
	v_mfma_f32_32x32x16_bf16 v[18:33], v[134:137], v[86:89], v[18:33]
	v_mfma_f32_32x32x16_bf16 v[34:49], v[134:137], v[90:93], v[34:49]
	v_mfma_f32_32x32x16_bf16 v[50:65], v[134:137], v[94:97], v[50:65]
	s_nop 15
	s_nop 7
	v_fmac_f32_e32 v2, v150, v153
	v_fmac_f32_e32 v18, v151, v155
	v_fmac_f32_e32 v34, v147, v152
	v_fmac_f32_e32 v50, v149, v154
	v_fmac_f32_e32 v2, v146, v152
	v_fmac_f32_e32 v18, v148, v154
	v_fmac_f32_e32 v34, v146, v153
	v_fmac_f32_e32 v50, v148, v155
	v_fmac_f32_e32 v3, v150, v34
	v_fmac_f32_e32 v19, v151, v50
	v_fmac_f32_e32 v35, v147, v2
	v_fmac_f32_e32 v51, v149, v18
	v_fmac_f32_e32 v3, v146, v2
	v_fmac_f32_e32 v19, v148, v18
	v_fmac_f32_e32 v35, v146, v34
	v_fmac_f32_e32 v51, v148, v50
	v_fmac_f32_e32 v4, v150, v35
	v_fmac_f32_e32 v20, v151, v51
	v_fmac_f32_e32 v36, v147, v3
	v_fmac_f32_e32 v52, v149, v19
	v_fmac_f32_e32 v4, v146, v3
	v_fmac_f32_e32 v20, v148, v19
	v_fmac_f32_e32 v36, v146, v35
	v_fmac_f32_e32 v52, v148, v51
	v_fmac_f32_e32 v5, v150, v36
	v_fmac_f32_e32 v21, v151, v52
	v_fmac_f32_e32 v37, v147, v4
	v_fmac_f32_e32 v53, v149, v20
	v_fmac_f32_e32 v5, v146, v4
	v_fmac_f32_e32 v21, v148, v20
	v_fmac_f32_e32 v37, v146, v36
	v_fmac_f32_e32 v53, v148, v52
	v_fmac_f32_e32 v6, v150, v37
	v_fmac_f32_e32 v22, v151, v53
	v_fmac_f32_e32 v38, v147, v5
	v_fmac_f32_e32 v54, v149, v21
	v_fmac_f32_e32 v6, v146, v5
	v_fmac_f32_e32 v22, v148, v21
	v_fmac_f32_e32 v38, v146, v37
	v_fmac_f32_e32 v54, v148, v53
	v_fmac_f32_e32 v7, v150, v38
	v_fmac_f32_e32 v23, v151, v54
	v_fmac_f32_e32 v39, v147, v6
	v_fmac_f32_e32 v55, v149, v22
	v_fmac_f32_e32 v7, v146, v6
	v_fmac_f32_e32 v23, v148, v22
	v_fmac_f32_e32 v39, v146, v38
	v_fmac_f32_e32 v55, v148, v54
	v_fmac_f32_e32 v8, v150, v39
	v_fmac_f32_e32 v24, v151, v55
	v_fmac_f32_e32 v40, v147, v7
	v_fmac_f32_e32 v56, v149, v23
	v_fmac_f32_e32 v8, v146, v7
	v_fmac_f32_e32 v24, v148, v23
	v_fmac_f32_e32 v40, v146, v39
	v_fmac_f32_e32 v56, v148, v55
	v_fmac_f32_e32 v9, v150, v40
	v_fmac_f32_e32 v25, v151, v56
	v_fmac_f32_e32 v41, v147, v8
	v_fmac_f32_e32 v57, v149, v24
	v_fmac_f32_e32 v9, v146, v8
	v_fmac_f32_e32 v25, v148, v24
	v_fmac_f32_e32 v41, v146, v40
	v_fmac_f32_e32 v57, v148, v56
	v_fmac_f32_e32 v10, v150, v41
	v_fmac_f32_e32 v26, v151, v57
	v_fmac_f32_e32 v42, v147, v9
	v_fmac_f32_e32 v58, v149, v25
	v_fmac_f32_e32 v10, v146, v9
	v_fmac_f32_e32 v26, v148, v25
	v_fmac_f32_e32 v42, v146, v41
	v_fmac_f32_e32 v58, v148, v57
	v_fmac_f32_e32 v11, v150, v42
	v_fmac_f32_e32 v27, v151, v58
	v_fmac_f32_e32 v43, v147, v10
	v_fmac_f32_e32 v59, v149, v26
	v_fmac_f32_e32 v11, v146, v10
	v_fmac_f32_e32 v27, v148, v26
	v_fmac_f32_e32 v43, v146, v42
	v_fmac_f32_e32 v59, v148, v58
	v_fmac_f32_e32 v12, v150, v43
	v_fmac_f32_e32 v28, v151, v59
	v_fmac_f32_e32 v44, v147, v11
	v_fmac_f32_e32 v60, v149, v27
	v_fmac_f32_e32 v12, v146, v11
	v_fmac_f32_e32 v28, v148, v27
	v_fmac_f32_e32 v44, v146, v43
	v_fmac_f32_e32 v60, v148, v59
	v_fmac_f32_e32 v13, v150, v44
	v_fmac_f32_e32 v29, v151, v60
	v_fmac_f32_e32 v45, v147, v12
	v_fmac_f32_e32 v61, v149, v28
	v_fmac_f32_e32 v13, v146, v12
	v_fmac_f32_e32 v29, v148, v28
	v_fmac_f32_e32 v45, v146, v44
	v_fmac_f32_e32 v61, v148, v60
	v_fmac_f32_e32 v14, v150, v45
	v_fmac_f32_e32 v30, v151, v61
	v_fmac_f32_e32 v46, v147, v13
	v_fmac_f32_e32 v62, v149, v29
	v_fmac_f32_e32 v14, v146, v13
	v_fmac_f32_e32 v30, v148, v29
	v_fmac_f32_e32 v46, v146, v45
	v_fmac_f32_e32 v62, v148, v61
	v_fmac_f32_e32 v15, v150, v46
	v_fmac_f32_e32 v31, v151, v62
	v_fmac_f32_e32 v47, v147, v14
	v_fmac_f32_e32 v63, v149, v30
	v_fmac_f32_e32 v15, v146, v14
	v_fmac_f32_e32 v31, v148, v30
	v_fmac_f32_e32 v47, v146, v46
	v_fmac_f32_e32 v63, v148, v62
	v_fmac_f32_e32 v16, v150, v47
	v_fmac_f32_e32 v32, v151, v63
	v_fmac_f32_e32 v48, v147, v15
	v_fmac_f32_e32 v64, v149, v31
	v_fmac_f32_e32 v16, v146, v15
	v_fmac_f32_e32 v32, v148, v31
	v_fmac_f32_e32 v48, v146, v47
	v_fmac_f32_e32 v64, v148, v63
	v_fmac_f32_e32 v17, v150, v48
	v_fmac_f32_e32 v33, v151, v64
	v_fmac_f32_e32 v49, v147, v16
	v_fmac_f32_e32 v65, v149, v32
	v_fmac_f32_e32 v17, v146, v16
	v_fmac_f32_e32 v33, v148, v32
	v_fmac_f32_e32 v49, v146, v48
	v_fmac_f32_e32 v65, v148, v64
	v_cvt_pk_bf16_f32 v226, v2, v34
	v_cvt_pk_bf16_f32 v227, v18, v50
	v_cvt_pk_bf16_f32 v228, v3, v35
	v_cvt_pk_bf16_f32 v229, v19, v51
	v_cvt_pk_bf16_f32 v230, v4, v36
	v_cvt_pk_bf16_f32 v231, v20, v52
	v_cvt_pk_bf16_f32 v232, v5, v37
	v_cvt_pk_bf16_f32 v233, v21, v53
	v_cvt_pk_bf16_f32 v234, v6, v38
	v_cvt_pk_bf16_f32 v235, v22, v54
	v_cvt_pk_bf16_f32 v236, v7, v39
	v_cvt_pk_bf16_f32 v237, v23, v55
	v_cvt_pk_bf16_f32 v238, v8, v40
	v_cvt_pk_bf16_f32 v239, v24, v56
	v_cvt_pk_bf16_f32 v240, v9, v41
	v_cvt_pk_bf16_f32 v241, v25, v57
	v_cvt_pk_bf16_f32 v242, v10, v42
	v_cvt_pk_bf16_f32 v243, v26, v58
	v_cvt_pk_bf16_f32 v244, v11, v43
	v_cvt_pk_bf16_f32 v245, v27, v59
	v_cvt_pk_bf16_f32 v246, v12, v44
	v_cvt_pk_bf16_f32 v247, v28, v60
	v_cvt_pk_bf16_f32 v248, v13, v45
	v_cvt_pk_bf16_f32 v249, v29, v61
	v_cvt_pk_bf16_f32 v250, v14, v46
	v_cvt_pk_bf16_f32 v251, v30, v62
	v_cvt_pk_bf16_f32 v252, v15, v47
	v_cvt_pk_bf16_f32 v253, v31, v63
	v_cvt_pk_bf16_f32 v210, v16, v48
	v_cvt_pk_bf16_f32 v211, v32, v64
	v_cvt_pk_bf16_f32 v212, v17, v49
	v_cvt_pk_bf16_f32 v213, v33, v65
	ds_write2_b32 v158, v226, v227 offset0:0 offset1:32
	ds_write2_b32 v158, v228, v229 offset0:68 offset1:100
	ds_write2_b32 v158, v230, v231 offset0:136 offset1:168
	ds_write2_b32 v158, v232, v233 offset0:204 offset1:236
	ds_write2_b32 v159, v234, v235 offset0:0 offset1:32
	ds_write2_b32 v159, v236, v237 offset0:68 offset1:100
	ds_write2_b32 v159, v238, v239 offset0:136 offset1:168
	ds_write2_b32 v159, v240, v241 offset0:204 offset1:236
	ds_write2_b32 v160, v242, v243 offset0:0 offset1:32
	ds_write2_b32 v160, v244, v245 offset0:68 offset1:100
	ds_write2_b32 v160, v246, v247 offset0:136 offset1:168
	ds_write2_b32 v160, v248, v249 offset0:204 offset1:236
	ds_write2_b32 v161, v250, v251 offset0:0 offset1:32
	ds_write2_b32 v161, v252, v253 offset0:68 offset1:100
	ds_write2_b32 v161, v210, v211 offset0:136 offset1:168
	ds_write2_b32 v161, v212, v213 offset0:204 offset1:236
	v_mov_b32_e32 v152, v17
	v_mov_b32_e32 v153, v49
	v_mov_b32_e32 v154, v33
	v_mov_b32_e32 v155, v65
	s_waitcnt lgkmcnt(0)
; template <bool BWD, int MODE  >
; __device__ __forceinline__ void ssm_pass(const bf16* proj, int rowbase, int g, const bf16x8* BBp, const bf16x8* CCp, float ar, float ai, float& sr, float& si,
;                                          LAS unsigned* XS, int lane, f32x4* ysc, const float* Dp, bf16* zbuf) {
;     ...
;     for (int c = 0; c < 16; ++c) {
;         const int ch = BWD ? 15 - c : c;
;         bf16x8 unext = ucur;
;         if (c < 15) unext = *(const bf16x8*)(up + (size_t)(BWD ? ch - 1 : ch + 1) * 32 * DIN);
;         f32x4 y0 = (f32x4){0.f, 0.f, 0.f, 0.f}, y1 = y0; bf16 uvl[8];
;         if (MODE == 2) {
;             y0 = ysc[(ch * 2 + 0) * 64 + lane]; y1 = ysc[(ch * 2 + 1) * 64 + lane];
; #pragma unroll
;             for (int q = 0; q < 8; ++q) uvl[q] = proj[(size_t)(rowbase + 32 * ch + 16 * (q >> 2) + 4 * (lane >> 4) + (q & 3)) * DIN + 768 + g * 16 + (lane & 15)];
;         }
;         f32x16 z16;
; #pragma unroll
;         for (int r = 0; r < 16; ++r) z16[r] = 0.f;
;         const f32x16 x0 = __builtin_amdgcn_mfma_f32_32x32x16_bf16(ucur, bb[0], z16, 0, 0, 0);
;         const f32x16 x1 = __builtin_amdgcn_mfma_f32_32x32x16_bf16(ucur, bb[1], z16, 0, 0, 0);
;         const f32x16 x2 = __builtin_amdgcn_mfma_f32_32x32x16_bf16(ucur, bb[2], z16, 0, 0, 0);
;         const f32x16 x3 = __builtin_amdgcn_mfma_f32_32x32x16_bf16(ucur, bb[3], z16, 0, 0, 0);
; #pragma unroll
;         for (int r = 0; r < 16; ++r) { const int t = crow(r, hi); XS[t * XS_STRIDE + ql] = pk2(x0[r], x2[r]); XS[t * XS_STRIDE + 32 + ql] = pk2(x1[r], x3[r]); }
;         LDS_FENCE();
; #pragma unroll
;         for (int tt = 0; tt < 32; ++tt) {
;             const int t = BWD ? 31 - tt : tt;
;     ...
;         if (MODE > 0) {
;             LDS_FENCE();
;             const LAS unsigned char* ab = (const LAS unsigned char*)XS + (lane & 15) * (XS_STRIDE * 4) + (lane >> 4) * 16;
; #pragma unroll
;             for (int kk = 0; kk < 4; ++kk) {
;                 const bf16x8 a0 = *(const LAS bf16x8*)(ab + kk * 64), a1 = *(const LAS bf16x8*)(ab + 16 * XS_STRIDE * 4 + kk * 64);
;                 y0 = __builtin_amdgcn_mfma_f32_16x16x32_bf16(a0, cc[kk], y0, 0, 0, 0);
;                 y1 = __builtin_amdgcn_mfma_f32_16x16x32_bf16(a1, cc[kk], y1, 0, 0, 0);
;             }
;             if (MODE == 1) { ysc[(ch * 2 + 0) * 64 + lane] = y0; ysc[(ch * 2 + 1) * 64 + lane] = y1; }
	ds_read_b128 v[226:229], v178 offset:0
	ds_read_b128 v[242:245], v178 offset:4352
	ds_read_b128 v[230:233], v178 offset:64
	ds_read_b128 v[246:249], v178 offset:4416
	ds_read_b128 v[234:237], v178 offset:128
	ds_read_b128 v[250:253], v178 offset:4480
	ds_read_b128 v[238:241], v178 offset:192
	ds_read_b128 v[210:213], v178 offset:4544
	s_waitcnt lgkmcnt(6)
	v_mfma_f32_16x16x32_bf16 v[180:183], v[226:229], v[98:101], 0
	v_mfma_f32_16x16x32_bf16 v[184:187], v[242:245], v[114:117], 0
	s_waitcnt lgkmcnt(4)
	v_mfma_f32_16x16x32_bf16 v[180:183], v[230:233], v[102:105], v[180:183]
	v_mfma_f32_16x16x32_bf16 v[184:187], v[246:249], v[118:121], v[184:187]
	s_waitcnt lgkmcnt(2)
	v_mfma_f32_16x16x32_bf16 v[180:183], v[234:237], v[106:109], v[180:183]
	v_mfma_f32_16x16x32_bf16 v[184:187], v[250:253], v[122:125], v[184:187]
	s_waitcnt lgkmcnt(0)
	v_mfma_f32_16x16x32_bf16 v[180:183], v[238:241], v[110:113], v[180:183]
	v_mfma_f32_16x16x32_bf16 v[184:187], v[210:213], v[126:129], v[184:187]
	s_waitcnt vmcnt(0)
	v_mov_b32_e32 v130, v138
	v_mov_b32_e32 v131, v139
	v_mov_b32_e32 v132, v140
	v_mov_b32_e32 v133, v141
	v_mov_b32_e32 v134, v142
	v_mov_b32_e32 v135, v143
	v_mov_b32_e32 v136, v144
	v_mov_b32_e32 v137, v145
	s_nop 7
	global_store_dwordx4 v0, v[180:183], s[78:79]
	global_store_dwordx4 v0, v[184:187], s[78:79] offset:1024
	s_add_u32 s78, s78, 0x800
	s_addc_u32 s79, s79, 0
	s_add_i32 s32, s32, 1
	s_cmp_lt_u32 s32, 3
	s_cbranch_scc1 .Lp3n_loopa
.Lp3n_loopa3:
	v_add_u32_e32 v156, v157, v156
	s_mov_b64 exec, s[60:61]
	global_load_dwordx4 v[138:141], v156, s[6:7]
	s_mov_b64 exec, s[62:63]
	global_load_dwordx4 v[142:145], v156, s[6:7]
	s_mov_b64 exec, -1
	v_mfma_f32_32x32x16_bf16 v[2:17], v[130:133], v[66:69], 0
	v_mfma_f32_32x32x16_bf16 v[18:33], v[130:133], v[70:73], 0
	v_mfma_f32_32x32x16_bf16 v[34:49], v[130:133], v[74:77], 0
	v_mfma_f32_32x32x16_bf16 v[50:65], v[130:133], v[78:81], 0
	v_mfma_f32_32x32x16_bf16 v[2:17], v[134:137], v[82:85], v[2:17]
	v_mfma_f32_32x32x16_bf16 v[18:33], v[134:137], v[86:89], v[18:33]
	v_mfma_f32_32x32x16_bf16 v[34:49], v[134:137], v[90:93], v[34:49]
	v_mfma_f32_32x32x16_bf16 v[50:65], v[134:137], v[94:97], v[50:65]
	s_nop 15
	s_nop 7
	v_fmac_f32_e32 v2, v150, v153
	v_fmac_f32_e32 v18, v151, v155
	v_fmac_f32_e32 v34, v147, v152
	v_fmac_f32_e32 v50, v149, v154
	v_fmac_f32_e32 v2, v146, v152
	v_fmac_f32_e32 v18, v148, v154
	v_fmac_f32_e32 v34, v146, v153
	v_fmac_f32_e32 v50, v148, v155
	v_fmac_f32_e32 v3, v150, v34
	v_fmac_f32_e32 v19, v151, v50
	v_fmac_f32_e32 v35, v147, v2
	v_fmac_f32_e32 v51, v149, v18
	v_fmac_f32_e32 v3, v146, v2
	v_fmac_f32_e32 v19, v148, v18
	v_fmac_f32_e32 v35, v146, v34
	v_fmac_f32_e32 v51, v148, v50
	v_fmac_f32_e32 v4, v150, v35
	v_fmac_f32_e32 v20, v151, v51
	v_fmac_f32_e32 v36, v147, v3
	v_fmac_f32_e32 v52, v149, v19
	v_fmac_f32_e32 v4, v146, v3
	v_fmac_f32_e32 v20, v148, v19
	v_fmac_f32_e32 v36, v146, v35
	v_fmac_f32_e32 v52, v148, v51
	v_fmac_f32_e32 v5, v150, v36
	v_fmac_f32_e32 v21, v151, v52
	v_fmac_f32_e32 v37, v147, v4
	v_fmac_f32_e32 v53, v149, v20
	v_fmac_f32_e32 v5, v146, v4
	v_fmac_f32_e32 v21, v148, v20
	v_fmac_f32_e32 v37, v146, v36
	v_fmac_f32_e32 v53, v148, v52
	v_fmac_f32_e32 v6, v150, v37
	v_fmac_f32_e32 v22, v151, v53
	v_fmac_f32_e32 v38, v147, v5
	v_fmac_f32_e32 v54, v149, v21
	v_fmac_f32_e32 v6, v146, v5
	v_fmac_f32_e32 v22, v148, v21
	v_fmac_f32_e32 v38, v146, v37
	v_fmac_f32_e32 v54, v148, v53
	v_fmac_f32_e32 v7, v150, v38
	v_fmac_f32_e32 v23, v151, v54
	v_fmac_f32_e32 v39, v147, v6
	v_fmac_f32_e32 v55, v149, v22
	v_fmac_f32_e32 v7, v146, v6
	v_fmac_f32_e32 v23, v148, v22
	v_fmac_f32_e32 v39, v146, v38
	v_fmac_f32_e32 v55, v148, v54
	v_fmac_f32_e32 v8, v150, v39
	v_fmac_f32_e32 v24, v151, v55
	v_fmac_f32_e32 v40, v147, v7
	v_fmac_f32_e32 v56, v149, v23
	v_fmac_f32_e32 v8, v146, v7
	v_fmac_f32_e32 v24, v148, v23
	v_fmac_f32_e32 v40, v146, v39
	v_fmac_f32_e32 v56, v148, v55
	v_fmac_f32_e32 v9, v150, v40
	v_fmac_f32_e32 v25, v151, v56
	v_fmac_f32_e32 v41, v147, v8
	v_fmac_f32_e32 v57, v149, v24
	v_fmac_f32_e32 v9, v146, v8
	v_fmac_f32_e32 v25, v148, v24
	v_fmac_f32_e32 v41, v146, v40
	v_fmac_f32_e32 v57, v148, v56
	v_fmac_f32_e32 v10, v150, v41
	v_fmac_f32_e32 v26, v151, v57
	v_fmac_f32_e32 v42, v147, v9
	v_fmac_f32_e32 v58, v149, v25
	v_fmac_f32_e32 v10, v146, v9
	v_fmac_f32_e32 v26, v148, v25
	v_fmac_f32_e32 v42, v146, v41
	v_fmac_f32_e32 v58, v148, v57
	v_fmac_f32_e32 v11, v150, v42
	v_fmac_f32_e32 v27, v151, v58
	v_fmac_f32_e32 v43, v147, v10
	v_fmac_f32_e32 v59, v149, v26
	v_fmac_f32_e32 v11, v146, v10
	v_fmac_f32_e32 v27, v148, v26
	v_fmac_f32_e32 v43, v146, v42
	v_fmac_f32_e32 v59, v148, v58
	v_fmac_f32_e32 v12, v150, v43
	v_fmac_f32_e32 v28, v151, v59
	v_fmac_f32_e32 v44, v147, v11
	v_fmac_f32_e32 v60, v149, v27
	v_fmac_f32_e32 v12, v146, v11
; #define LAS __attribute__((address_space(3)))
; __device__ __forceinline__ unsigned pk2(float lo, float hi) { const f32x2 v = {lo, hi}; return __builtin_bit_cast(unsigned, __builtin_convertvector(v, bf16x2_t)); }
; __device__ __forceinline__ float bflo(unsigned w) { return __uint_as_float(w << 16); }
; __device__ __forceinline__ float bfhi(unsigned w) { return __uint_as_float(w & 0xffff0000u); }
; #define LDS_FENCE() asm volatile("s_waitcnt lgkmcnt(0)" ::: "memory")
; __device__ __forceinline__ int crow(int r, int hi) { return (r & 3) + 8 * (r >> 2) + 4 * hi; }
; template <bool BWD, int MODE  >
; __device__ __forceinline__ void ssm_pass(const bf16* proj, int rowbase, int g, const bf16x8* BBp, const bf16x8* CCp, float ar, float ai, float& sr, float& si,
;                                          LAS unsigned* XS, int lane, f32x4* ysc, const float* Dp, bf16* zbuf) {
;     ...
;         for (int r = 0; r < 16; ++r) { const int t = crow(r, hi); XS[t * XS_STRIDE + ql] = pk2(x0[r], x2[r]); XS[t * XS_STRIDE + 32 + ql] = pk2(x1[r], x3[r]); }
;         LDS_FENCE();
; #pragma unroll
;         for (int tt = 0; tt < 32; ++tt) {
;             const int t = BWD ? 31 - tt : tt;
;             const unsigned v = XS[t * XS_STRIDE + lane];
;             const float nr = fmaf(ar, sr, fmaf(-ai, si, bflo(v))), ni = fmaf(ar, si, fmaf(ai, sr, bfhi(v)));
;             sr = nr; si = ni;
;             if (MODE > 0) XS[t * XS_STRIDE + lane] = pk2(sr, si);
;         }
;         if (MODE > 0) {
;             LDS_FENCE();
;             const LAS unsigned char* ab = (const LAS unsigned char*)XS + (lane & 15) * (XS_STRIDE * 4) + (lane >> 4) * 16;
; #pragma unroll
;             for (int kk = 0; kk < 4; ++kk) {
;                 const bf16x8 a0 = *(const LAS bf16x8*)(ab + kk * 64), a1 = *(const LAS bf16x8*)(ab + 16 * XS_STRIDE * 4 + kk * 64);
;                 y0 = __builtin_amdgcn_mfma_f32_16x16x32_bf16(a0, cc[kk], y0, 0, 0, 0);
;                 y1 = __builtin_amdgcn_mfma_f32_16x16x32_bf16(a1, cc[kk], y1, 0, 0, 0);
;             }
;             if (MODE == 1) { ysc[(ch * 2 + 0) * 64 + lane] = y0; ysc[(ch * 2 + 1) * 64 + lane] = y1; }
	v_fmac_f32_e32 v28, v148, v27
	v_fmac_f32_e32 v44, v146, v43
	v_fmac_f32_e32 v60, v148, v59
	v_fmac_f32_e32 v13, v150, v44
	v_fmac_f32_e32 v29, v151, v60
	v_fmac_f32_e32 v45, v147, v12
	v_fmac_f32_e32 v61, v149, v28
	v_fmac_f32_e32 v13, v146, v12
	v_fmac_f32_e32 v29, v148, v28
	v_fmac_f32_e32 v45, v146, v44
	v_fmac_f32_e32 v61, v148, v60
	v_fmac_f32_e32 v14, v150, v45
	v_fmac_f32_e32 v30, v151, v61
	v_fmac_f32_e32 v46, v147, v13
	v_fmac_f32_e32 v62, v149, v29
	v_fmac_f32_e32 v14, v146, v13
	v_fmac_f32_e32 v30, v148, v29
	v_fmac_f32_e32 v46, v146, v45
	v_fmac_f32_e32 v62, v148, v61
	v_fmac_f32_e32 v15, v150, v46
	v_fmac_f32_e32 v31, v151, v62
	v_fmac_f32_e32 v47, v147, v14
	v_fmac_f32_e32 v63, v149, v30
	v_fmac_f32_e32 v15, v146, v14
	v_fmac_f32_e32 v31, v148, v30
	v_fmac_f32_e32 v47, v146, v46
	v_fmac_f32_e32 v63, v148, v62
	v_fmac_f32_e32 v16, v150, v47
	v_fmac_f32_e32 v32, v151, v63
	v_fmac_f32_e32 v48, v147, v15
	v_fmac_f32_e32 v64, v149, v31
	v_fmac_f32_e32 v16, v146, v15
	v_fmac_f32_e32 v32, v148, v31
	v_fmac_f32_e32 v48, v146, v47
	v_fmac_f32_e32 v64, v148, v63
	v_fmac_f32_e32 v17, v150, v48
	v_fmac_f32_e32 v33, v151, v64
	v_fmac_f32_e32 v49, v147, v16
	v_fmac_f32_e32 v65, v149, v32
	v_fmac_f32_e32 v17, v146, v16
	v_fmac_f32_e32 v33, v148, v32
	v_fmac_f32_e32 v49, v146, v48
	v_fmac_f32_e32 v65, v148, v64
	v_cvt_pk_bf16_f32 v226, v2, v34
	v_cvt_pk_bf16_f32 v227, v18, v50
	v_cvt_pk_bf16_f32 v228, v3, v35
	v_cvt_pk_bf16_f32 v229, v19, v51
	v_cvt_pk_bf16_f32 v230, v4, v36
	v_cvt_pk_bf16_f32 v231, v20, v52
	v_cvt_pk_bf16_f32 v232, v5, v37
	v_cvt_pk_bf16_f32 v233, v21, v53
	v_cvt_pk_bf16_f32 v234, v6, v38
	v_cvt_pk_bf16_f32 v235, v22, v54
	v_cvt_pk_bf16_f32 v236, v7, v39
	v_cvt_pk_bf16_f32 v237, v23, v55
	v_cvt_pk_bf16_f32 v238, v8, v40
	v_cvt_pk_bf16_f32 v239, v24, v56
	v_cvt_pk_bf16_f32 v240, v9, v41
	v_cvt_pk_bf16_f32 v241, v25, v57
	v_cvt_pk_bf16_f32 v242, v10, v42
	v_cvt_pk_bf16_f32 v243, v26, v58
	v_cvt_pk_bf16_f32 v244, v11, v43
	v_cvt_pk_bf16_f32 v245, v27, v59
	v_cvt_pk_bf16_f32 v246, v12, v44
	v_cvt_pk_bf16_f32 v247, v28, v60
	v_cvt_pk_bf16_f32 v248, v13, v45
	v_cvt_pk_bf16_f32 v249, v29, v61
	v_cvt_pk_bf16_f32 v250, v14, v46
	v_cvt_pk_bf16_f32 v251, v30, v62
	v_cvt_pk_bf16_f32 v252, v15, v47
	v_cvt_pk_bf16_f32 v253, v31, v63
	v_cvt_pk_bf16_f32 v210, v16, v48
	v_cvt_pk_bf16_f32 v211, v32, v64
	v_cvt_pk_bf16_f32 v212, v17, v49
	v_cvt_pk_bf16_f32 v213, v33, v65
	ds_write2_b32 v158, v226, v227 offset0:0 offset1:32
	ds_write2_b32 v158, v228, v229 offset0:68 offset1:100
	ds_write2_b32 v158, v230, v231 offset0:136 offset1:168
	ds_write2_b32 v158, v232, v233 offset0:204 offset1:236
	ds_write2_b32 v159, v234, v235 offset0:0 offset1:32
	ds_write2_b32 v159, v236, v237 offset0:68 offset1:100
	ds_write2_b32 v159, v238, v239 offset0:136 offset1:168
	ds_write2_b32 v159, v240, v241 offset0:204 offset1:236
	ds_write2_b32 v160, v242, v243 offset0:0 offset1:32
	ds_write2_b32 v160, v244, v245 offset0:68 offset1:100
	ds_write2_b32 v160, v246, v247 offset0:136 offset1:168
	ds_write2_b32 v160, v248, v249 offset0:204 offset1:236
	ds_write2_b32 v161, v250, v251 offset0:0 offset1:32
	ds_write2_b32 v161, v252, v253 offset0:68 offset1:100
	ds_write2_b32 v161, v210, v211 offset0:136 offset1:168
	ds_write2_b32 v161, v212, v213 offset0:204 offset1:236
	v_mov_b32_e32 v152, v17
	v_mov_b32_e32 v153, v49
	v_mov_b32_e32 v154, v33
	v_mov_b32_e32 v155, v65
	s_waitcnt lgkmcnt(0)
	ds_read_b128 v[226:229], v178 offset:0
	ds_read_b128 v[242:245], v178 offset:4352
	ds_read_b128 v[230:233], v178 offset:64
	ds_read_b128 v[246:249], v178 offset:4416
	ds_read_b128 v[234:237], v178 offset:128
	ds_read_b128 v[250:253], v178 offset:4480
	ds_read_b128 v[238:241], v178 offset:192
	ds_read_b128 v[210:213], v178 offset:4544
	s_waitcnt lgkmcnt(6)
	v_mfma_f32_16x16x32_bf16 v[180:183], v[226:229], v[98:101], 0
	v_mfma_f32_16x16x32_bf16 v[184:187], v[242:245], v[114:117], 0
	s_waitcnt lgkmcnt(4)
	v_mfma_f32_16x16x32_bf16 v[180:183], v[230:233], v[102:105], v[180:183]
	v_mfma_f32_16x16x32_bf16 v[184:187], v[246:249], v[118:121], v[184:187]
	s_waitcnt lgkmcnt(2)
	v_mfma_f32_16x16x32_bf16 v[180:183], v[234:237], v[106:109], v[180:183]
	v_mfma_f32_16x16x32_bf16 v[184:187], v[250:253], v[122:125], v[184:187]
	s_waitcnt lgkmcnt(0)
	v_mfma_f32_16x16x32_bf16 v[180:183], v[238:241], v[110:113], v[180:183]
	v_mfma_f32_16x16x32_bf16 v[184:187], v[210:213], v[126:129], v[184:187]
	s_waitcnt vmcnt(0)
	v_mov_b32_e32 v130, v138
	v_mov_b32_e32 v131, v139
	v_mov_b32_e32 v132, v140
	v_mov_b32_e32 v133, v141
	v_mov_b32_e32 v134, v142
	v_mov_b32_e32 v135, v143
	v_mov_b32_e32 v136, v144
	v_mov_b32_e32 v137, v145
	s_nop 7
	s_lshl_b32 s26, s18, 11
	s_add_i32 s26, s26, 0x15000
	v_add_u32_e32 v179, s26, v0
	ds_write_b128 v179, v[180:183]
	ds_write_b128 v179, v[184:187] offset:1024
	s_add_i32 s32, s32, 1

; __device__ __forceinline__ unsigned pk2(float lo, float hi) { const f32x2 v = {lo, hi}; return __builtin_bit_cast(unsigned, __builtin_convertvector(v, bf16x2_t)); }
; __device__ __forceinline__ float bflo(unsigned w) { return __uint_as_float(w << 16); }
; __device__ __forceinline__ float bfhi(unsigned w) { return __uint_as_float(w & 0xffff0000u); }
; #define LDS_FENCE() asm volatile("s_waitcnt lgkmcnt(0)" ::: "memory")
; template <bool BWD, int MODE  >
; __device__ __forceinline__ void ssm_pass(const bf16* proj, int rowbase, int g, const bf16x8* BBp, const bf16x8* CCp, float ar, float ai, float& sr, float& si,
;                                          LAS unsigned* XS, int lane, f32x4* ysc, const float* Dp, bf16* zbuf) {
;     ...
;     for (int c = 0; c < 16; ++c) {
;         const int ch = BWD ? 15 - c : c;
;         bf16x8 unext = ucur;
;         if (c < 15) unext = *(const bf16x8*)(up + (size_t)(BWD ? ch - 1 : ch + 1) * 32 * DIN);
;         f32x4 y0 = (f32x4){0.f, 0.f, 0.f, 0.f}, y1 = y0; bf16 uvl[8];
;         if (MODE == 2) {
;             y0 = ysc[(ch * 2 + 0) * 64 + lane]; y1 = ysc[(ch * 2 + 1) * 64 + lane];
; #pragma unroll
;             for (int q = 0; q < 8; ++q) uvl[q] = proj[(size_t)(rowbase + 32 * ch + 16 * (q >> 2) + 4 * (lane >> 4) + (q & 3)) * DIN + 768 + g * 16 + (lane & 15)];
;         }
;         f32x16 z16;
; #pragma unroll
;         for (int r = 0; r < 16; ++r) z16[r] = 0.f;
;         const f32x16 x0 = __builtin_amdgcn_mfma_f32_32x32x16_bf16(ucur, bb[0], z16, 0, 0, 0);
;         const f32x16 x1 = __builtin_amdgcn_mfma_f32_32x32x16_bf16(ucur, bb[1], z16, 0, 0, 0);
;         const f32x16 x2 = __builtin_amdgcn_mfma_f32_32x32x16_bf16(ucur, bb[2], z16, 0, 0, 0);
;         const f32x16 x3 = __builtin_amdgcn_mfma_f32_32x32x16_bf16(ucur, bb[3], z16, 0, 0, 0);
; #pragma unroll
;         for (int r = 0; r < 16; ++r) { const int t = crow(r, hi); XS[t * XS_STRIDE + ql] = pk2(x0[r], x2[r]); XS[t * XS_STRIDE + 32 + ql] = pk2(x1[r], x3[r]); }
;         LDS_FENCE();
; #pragma unroll
;         for (int tt = 0; tt < 32; ++tt) {
;             const int t = BWD ? 31 - tt : tt;
;             const unsigned v = XS[t * XS_STRIDE + lane];
;             const float nr = fmaf(ar, sr, fmaf(-ai, si, bflo(v))), ni = fmaf(ar, si, fmaf(ai, sr, bfhi(v)));
;             sr = nr; si = ni;
;             if (MODE > 0) XS[t * XS_STRIDE + lane] = pk2(sr, si);
.Lp3n_nopfb4:
	s_lshl_b32 s26, s18, 11
	s_add_i32 s26, s26, 0x15000
	v_add_u32_e32 v179, s26, v225
	ds_read_b128 v[188:191], v179 offset:1024
	ds_read_b128 v[192:195], v179
	global_load_ushort v196, v206, s[6:7]
	global_load_ushort v197, v206, s[6:7] offset:2560
	global_load_ushort v198, v206, s[80:81]
	global_load_ushort v199, v206, s[80:81] offset:2560
	global_load_ushort v200, v207, s[6:7]
	global_load_ushort v201, v207, s[6:7] offset:-2560
	global_load_ushort v202, v207, s[82:83]
	global_load_ushort v203, v207, s[82:83] offset:-2560
	v_mfma_f32_32x32x16_bf16 v[2:17], v[130:133], v[66:69], 0
	v_mfma_f32_32x32x16_bf16 v[18:33], v[130:133], v[70:73], 0
	v_mfma_f32_32x32x16_bf16 v[34:49], v[130:133], v[74:77], 0
	v_mfma_f32_32x32x16_bf16 v[50:65], v[130:133], v[78:81], 0
	v_mfma_f32_32x32x16_bf16 v[2:17], v[134:137], v[82:85], v[2:17]
	v_mfma_f32_32x32x16_bf16 v[18:33], v[134:137], v[86:89], v[18:33]
	v_mfma_f32_32x32x16_bf16 v[34:49], v[134:137], v[90:93], v[34:49]
	v_mfma_f32_32x32x16_bf16 v[50:65], v[134:137], v[94:97], v[50:65]
	s_nop 15
	s_nop 7
	v_fmac_f32_e32 v2, v150, v153
	v_fmac_f32_e32 v18, v151, v155
	v_fmac_f32_e32 v34, v147, v152
	v_fmac_f32_e32 v50, v149, v154
	v_fmac_f32_e32 v2, v146, v152
	v_fmac_f32_e32 v18, v148, v154
	v_fmac_f32_e32 v34, v146, v153
	v_fmac_f32_e32 v50, v148, v155
	v_fmac_f32_e32 v3, v150, v34
	v_fmac_f32_e32 v19, v151, v50
	v_fmac_f32_e32 v35, v147, v2
	v_fmac_f32_e32 v51, v149, v18
	v_fmac_f32_e32 v3, v146, v2
	v_fmac_f32_e32 v19, v148, v18
	v_fmac_f32_e32 v35, v146, v34
	v_fmac_f32_e32 v51, v148, v50
	v_fmac_f32_e32 v4, v150, v35
	v_fmac_f32_e32 v20, v151, v51
	v_fmac_f32_e32 v36, v147, v3
	v_fmac_f32_e32 v52, v149, v19
	v_fmac_f32_e32 v4, v146, v3
	v_fmac_f32_e32 v20, v148, v19
	v_fmac_f32_e32 v36, v146, v35
	v_fmac_f32_e32 v52, v148, v51
	v_fmac_f32_e32 v5, v150, v36
	v_fmac_f32_e32 v21, v151, v52
	v_fmac_f32_e32 v37, v147, v4
	v_fmac_f32_e32 v53, v149, v20
	v_fmac_f32_e32 v5, v146, v4
	v_fmac_f32_e32 v21, v148, v20
	v_fmac_f32_e32 v37, v146, v36
	v_fmac_f32_e32 v53, v148, v52
	v_fmac_f32_e32 v6, v150, v37
	v_fmac_f32_e32 v22, v151, v53
	v_fmac_f32_e32 v38, v147, v5
	v_fmac_f32_e32 v54, v149, v21
	v_fmac_f32_e32 v6, v146, v5
	v_fmac_f32_e32 v22, v148, v21
	v_fmac_f32_e32 v38, v146, v37
	v_fmac_f32_e32 v54, v148, v53
	v_fmac_f32_e32 v7, v150, v38
	v_fmac_f32_e32 v23, v151, v54
	v_fmac_f32_e32 v39, v147, v6
	v_fmac_f32_e32 v55, v149, v22
	v_fmac_f32_e32 v7, v146, v6
	v_fmac_f32_e32 v23, v148, v22
	v_fmac_f32_e32 v39, v146, v38
	v_fmac_f32_e32 v55, v148, v54
	v_fmac_f32_e32 v8, v150, v39
	v_fmac_f32_e32 v24, v151, v55
	v_fmac_f32_e32 v40, v147, v7
	v_fmac_f32_e32 v56, v149, v23
	v_fmac_f32_e32 v8, v146, v7
	v_fmac_f32_e32 v24, v148, v23
	v_fmac_f32_e32 v40, v146, v39
	v_fmac_f32_e32 v56, v148, v55
	v_fmac_f32_e32 v9, v150, v40
	v_fmac_f32_e32 v25, v151, v56
	v_fmac_f32_e32 v41, v147, v8
	v_fmac_f32_e32 v57, v149, v24
	v_fmac_f32_e32 v9, v146, v8
	v_fmac_f32_e32 v25, v148, v24
	v_fmac_f32_e32 v41, v146, v40
	v_fmac_f32_e32 v57, v148, v56
	v_fmac_f32_e32 v10, v150, v41
	v_fmac_f32_e32 v26, v151, v57
	v_fmac_f32_e32 v42, v147, v9
	v_fmac_f32_e32 v58, v149, v25
	v_fmac_f32_e32 v10, v146, v9
	v_fmac_f32_e32 v26, v148, v25
	v_fmac_f32_e32 v42, v146, v41
	v_fmac_f32_e32 v58, v148, v57
	v_fmac_f32_e32 v11, v150, v42
	v_fmac_f32_e32 v27, v151, v58
	v_fmac_f32_e32 v43, v147, v10
	v_fmac_f32_e32 v59, v149, v26
	v_fmac_f32_e32 v11, v146, v10
	v_fmac_f32_e32 v27, v148, v26
	v_fmac_f32_e32 v43, v146, v42
	v_fmac_f32_e32 v59, v148, v58
	v_fmac_f32_e32 v12, v150, v43
	v_fmac_f32_e32 v28, v151, v59
	v_fmac_f32_e32 v44, v147, v11
	v_fmac_f32_e32 v60, v149, v27
	v_fmac_f32_e32 v12, v146, v11
	v_fmac_f32_e32 v28, v148, v27
	v_fmac_f32_e32 v44, v146, v43
	v_fmac_f32_e32 v60, v148, v59
	v_fmac_f32_e32 v13, v150, v44
	v_fmac_f32_e32 v29, v151, v60
	v_fmac_f32_e32 v45, v147, v12
	v_fmac_f32_e32 v61, v149, v28
	v_fmac_f32_e32 v13, v146, v12
	v_fmac_f32_e32 v29, v148, v28
	v_fmac_f32_e32 v45, v146, v44
	v_fmac_f32_e32 v61, v148, v60
	v_fmac_f32_e32 v14, v150, v45
	v_fmac_f32_e32 v30, v151, v61
	v_fmac_f32_e32 v46, v147, v13
	v_fmac_f32_e32 v62, v149, v29
	v_fmac_f32_e32 v14, v146, v13
	v_fmac_f32_e32 v30, v148, v29
	v_fmac_f32_e32 v46, v146, v45
	v_fmac_f32_e32 v62, v148, v61
	v_fmac_f32_e32 v15, v150, v46
	v_fmac_f32_e32 v31, v151, v62
	v_fmac_f32_e32 v47, v147, v14
	v_fmac_f32_e32 v63, v149, v30
	v_fmac_f32_e32 v15, v146, v14
	v_fmac_f32_e32 v31, v148, v30
	v_fmac_f32_e32 v47, v146, v46
	v_fmac_f32_e32 v63, v148, v62
	v_fmac_f32_e32 v16, v150, v47
	v_fmac_f32_e32 v32, v151, v63
	v_fmac_f32_e32 v48, v147, v15
	v_fmac_f32_e32 v64, v149, v31
	v_fmac_f32_e32 v16, v146, v15
	v_fmac_f32_e32 v32, v148, v31
	v_fmac_f32_e32 v48, v146, v47
	v_fmac_f32_e32 v64, v148, v63
	v_fmac_f32_e32 v17, v150, v48
	v_fmac_f32_e32 v33, v151, v64
	v_fmac_f32_e32 v49, v147, v16
	v_fmac_f32_e32 v65, v149, v32
	v_fmac_f32_e32 v17, v146, v16
	v_fmac_f32_e32 v33, v148, v32
	v_fmac_f32_e32 v49, v146, v48
	v_fmac_f32_e32 v65, v148, v64
	v_cvt_pk_bf16_f32 v226, v2, v34
	v_cvt_pk_bf16_f32 v227, v18, v50
	v_cvt_pk_bf16_f32 v228, v3, v35
	v_cvt_pk_bf16_f32 v229, v19, v51
	v_cvt_pk_bf16_f32 v230, v4, v36
	v_cvt_pk_bf16_f32 v231, v20, v52
	v_cvt_pk_bf16_f32 v232, v5, v37
	v_cvt_pk_bf16_f32 v233, v21, v53
	v_cvt_pk_bf16_f32 v234, v6, v38
	v_cvt_pk_bf16_f32 v235, v22, v54
	v_cvt_pk_bf16_f32 v236, v7, v39
	v_cvt_pk_bf16_f32 v237, v23, v55
	v_cvt_pk_bf16_f32 v238, v8, v40
	v_cvt_pk_bf16_f32 v239, v24, v56
	v_cvt_pk_bf16_f32 v240, v9, v41
	v_cvt_pk_bf16_f32 v241, v25, v57
	v_cvt_pk_bf16_f32 v242, v10, v42
	v_cvt_pk_bf16_f32 v243, v26, v58
	v_cvt_pk_bf16_f32 v244, v11, v43
; #define LAS __attribute__((address_space(3)))
; __device__ __forceinline__ unsigned f2bf(float f) { unsigned u = __builtin_bit_cast(unsigned, f); return (u + 0x7fffu + ((u >> 16) & 1u)) >> 16; }
; __device__ __forceinline__ float bf2f(bf16 v) { return __uint_as_float((unsigned)v << 16); }
; #define LDS_FENCE() asm volatile("s_waitcnt lgkmcnt(0)" ::: "memory")
; template <bool BWD, int MODE  >
; __device__ __forceinline__ void ssm_pass(const bf16* proj, int rowbase, int g, const bf16x8* BBp, const bf16x8* CCp, float ar, float ai, float& sr, float& si,
;                                          LAS unsigned* XS, int lane, f32x4* ysc, const float* Dp, bf16* zbuf) {
;     ...
;         if (MODE > 0) {
;             LDS_FENCE();
;             const LAS unsigned char* ab = (const LAS unsigned char*)XS + (lane & 15) * (XS_STRIDE * 4) + (lane >> 4) * 16;
; #pragma unroll
;             for (int kk = 0; kk < 4; ++kk) {
;                 const bf16x8 a0 = *(const LAS bf16x8*)(ab + kk * 64), a1 = *(const LAS bf16x8*)(ab + 16 * XS_STRIDE * 4 + kk * 64);
;                 y0 = __builtin_amdgcn_mfma_f32_16x16x32_bf16(a0, cc[kk], y0, 0, 0, 0);
;                 y1 = __builtin_amdgcn_mfma_f32_16x16x32_bf16(a1, cc[kk], y1, 0, 0, 0);
;             }
;             if (MODE == 1) { ysc[(ch * 2 + 0) * 64 + lane] = y0; ysc[(ch * 2 + 1) * 64 + lane] = y1; }
;             else {
;                 const int hcol = g * 16 + (lane & 15);
; #pragma unroll
;                 for (int rt = 0; rt < 2; ++rt)
; #pragma unroll
;                     for (int i = 0; i < 4; ++i) {
;                         const int row = rowbase + 32 * ch + 16 * rt + 4 * (lane >> 4) + i;
;                         const float uv = bf2f(uvl[rt * 4 + i]);
;                         const float y = (rt ? y1[i] : y0[i]) + dval * uv;
;                         const float zz = y * __builtin_amdgcn_rcpf(1.0f + __builtin_amdgcn_exp2f(-2.3022082f * (y + 0.044715f * y * y * y)));
;                         zbuf[(size_t)row * 512 + hcol] = (bf16)f2bf(zz);
;                     }
	v_cvt_pk_bf16_f32 v245, v27, v59
	v_cvt_pk_bf16_f32 v246, v12, v44
	v_cvt_pk_bf16_f32 v247, v28, v60
	v_cvt_pk_bf16_f32 v248, v13, v45
	v_cvt_pk_bf16_f32 v249, v29, v61
	v_cvt_pk_bf16_f32 v250, v14, v46
	v_cvt_pk_bf16_f32 v251, v30, v62
	v_cvt_pk_bf16_f32 v252, v15, v47
	v_cvt_pk_bf16_f32 v253, v31, v63
	v_cvt_pk_bf16_f32 v210, v16, v48
	v_cvt_pk_bf16_f32 v211, v32, v64
	v_cvt_pk_bf16_f32 v212, v17, v49
	v_cvt_pk_bf16_f32 v213, v33, v65
	ds_write2_b32 v158, v226, v227 offset0:0 offset1:32
	ds_write2_b32 v158, v228, v229 offset0:68 offset1:100
	ds_write2_b32 v158, v230, v231 offset0:136 offset1:168
	ds_write2_b32 v158, v232, v233 offset0:204 offset1:236
	ds_write2_b32 v159, v234, v235 offset0:0 offset1:32
	ds_write2_b32 v159, v236, v237 offset0:68 offset1:100
	ds_write2_b32 v159, v238, v239 offset0:136 offset1:168
	ds_write2_b32 v159, v240, v241 offset0:204 offset1:236
	ds_write2_b32 v160, v242, v243 offset0:0 offset1:32
	ds_write2_b32 v160, v244, v245 offset0:68 offset1:100
	ds_write2_b32 v160, v246, v247 offset0:136 offset1:168
	ds_write2_b32 v160, v248, v249 offset0:204 offset1:236
	ds_write2_b32 v161, v250, v251 offset0:0 offset1:32
	ds_write2_b32 v161, v252, v253 offset0:68 offset1:100
	ds_write2_b32 v161, v210, v211 offset0:136 offset1:168
	ds_write2_b32 v161, v212, v213 offset0:204 offset1:236
	v_mov_b32_e32 v152, v17
	v_mov_b32_e32 v153, v49
	v_mov_b32_e32 v154, v33
	v_mov_b32_e32 v155, v65
	s_waitcnt lgkmcnt(0)
	ds_read_b128 v[226:229], v178 offset:0
	ds_read_b128 v[242:245], v178 offset:4352
	ds_read_b128 v[230:233], v178 offset:64
	ds_read_b128 v[246:249], v178 offset:4416
	ds_read_b128 v[234:237], v178 offset:128
	ds_read_b128 v[250:253], v178 offset:4480
	ds_read_b128 v[238:241], v178 offset:192
	ds_read_b128 v[210:213], v178 offset:4544
	s_waitcnt lgkmcnt(6)
	v_mfma_f32_16x16x32_bf16 v[180:183], v[226:229], v[98:101], 0
	v_mfma_f32_16x16x32_bf16 v[184:187], v[242:245], v[114:117], 0
	s_waitcnt lgkmcnt(4)
	v_mfma_f32_16x16x32_bf16 v[180:183], v[230:233], v[102:105], v[180:183]
	v_mfma_f32_16x16x32_bf16 v[184:187], v[246:249], v[118:121], v[184:187]
	s_waitcnt lgkmcnt(2)
	v_mfma_f32_16x16x32_bf16 v[180:183], v[234:237], v[106:109], v[180:183]
	v_mfma_f32_16x16x32_bf16 v[184:187], v[250:253], v[122:125], v[184:187]
	s_waitcnt lgkmcnt(0)
	v_mfma_f32_16x16x32_bf16 v[180:183], v[238:241], v[110:113], v[180:183]
	v_mfma_f32_16x16x32_bf16 v[184:187], v[210:213], v[126:129], v[184:187]
	s_waitcnt vmcnt(0)
	v_mov_b32_e32 v130, v138
	v_mov_b32_e32 v131, v139
	v_mov_b32_e32 v132, v140
	v_mov_b32_e32 v133, v141
	v_mov_b32_e32 v134, v142
	v_mov_b32_e32 v135, v143
	v_mov_b32_e32 v136, v144
	v_mov_b32_e32 v137, v145
	s_nop 7
	v_add_f32_e32 v180, v180, v191
	v_add_f32_e32 v181, v181, v190
	v_add_f32_e32 v182, v182, v189
	v_add_f32_e32 v183, v183, v188
	v_add_f32_e32 v184, v184, v195
	v_add_f32_e32 v185, v185, v194
	v_add_f32_e32 v186, v186, v193
	v_add_f32_e32 v187, v187, v192
	v_lshlrev_b32_e32 v196, 16, v196
	v_lshlrev_b32_e32 v197, 16, v197
	v_lshlrev_b32_e32 v198, 16, v198
	v_lshlrev_b32_e32 v199, 16, v199
	v_lshlrev_b32_e32 v200, 16, v200
	v_lshlrev_b32_e32 v201, 16, v201
	v_lshlrev_b32_e32 v202, 16, v202
	v_lshlrev_b32_e32 v203, 16, v203
	v_fmac_f32_e32 v180, v208, v196
	v_fmac_f32_e32 v181, v208, v197
	v_fmac_f32_e32 v182, v208, v198
	v_fmac_f32_e32 v183, v208, v199
	v_fmac_f32_e32 v184, v208, v200
	v_fmac_f32_e32 v185, v208, v201
	v_fmac_f32_e32 v186, v208, v202
	v_fmac_f32_e32 v187, v208, v203
	v_mul_f32_e32 v226, 0x3d372713, v180
	v_mul_f32_e32 v227, 0x3d372713, v181
	v_mul_f32_e32 v228, 0x3d372713, v182
	v_mul_f32_e32 v229, 0x3d372713, v183
	v_mul_f32_e32 v230, 0x3d372713, v184
	v_mul_f32_e32 v231, 0x3d372713, v185
	v_mul_f32_e32 v232, 0x3d372713, v186
	v_mul_f32_e32 v233, 0x3d372713, v187
	v_mul_f32_e32 v226, v180, v226
	v_mul_f32_e32 v227, v181, v227
	v_mul_f32_e32 v228, v182, v228
	v_mul_f32_e32 v229, v183, v229
	v_mul_f32_e32 v230, v184, v230
	v_mul_f32_e32 v231, v185, v231
	v_mul_f32_e32 v232, v186, v232
	v_mul_f32_e32 v233, v187, v233
	v_fma_f32 v226, v180, v226, v180
	v_fma_f32 v227, v181, v227, v181
	v_fma_f32 v228, v182, v228, v182
	v_fma_f32 v229, v183, v229, v183
	v_fma_f32 v230, v184, v230, v184
	v_fma_f32 v231, v185, v231, v185
	v_fma_f32 v232, v186, v232, v186
	v_fma_f32 v233, v187, v233, v187
	v_mul_f32_e32 v226, 0xc0135761, v226
	v_mul_f32_e32 v227, 0xc0135761, v227
	v_mul_f32_e32 v228, 0xc0135761, v228
	v_mul_f32_e32 v229, 0xc0135761, v229
	v_mul_f32_e32 v230, 0xc0135761, v230
	v_mul_f32_e32 v231, 0xc0135761, v231
	v_mul_f32_e32 v232, 0xc0135761, v232
	v_mul_f32_e32 v233, 0xc0135761, v233
	v_exp_f32_e32 v226, v226
	v_exp_f32_e32 v227, v227
	v_exp_f32_e32 v228, v228
	v_exp_f32_e32 v229, v229
	v_exp_f32_e32 v230, v230
	v_exp_f32_e32 v231, v231
	v_exp_f32_e32 v232, v232
	v_exp_f32_e32 v233, v233
	v_add_f32_e32 v226, 1.0, v226
	v_add_f32_e32 v227, 1.0, v227
	v_add_f32_e32 v228, 1.0, v228
	v_add_f32_e32 v229, 1.0, v229
	v_add_f32_e32 v230, 1.0, v230
	v_add_f32_e32 v231, 1.0, v231
	v_add_f32_e32 v232, 1.0, v232
	v_add_f32_e32 v233, 1.0, v233
	v_rcp_f32_e32 v226, v226
	v_rcp_f32_e32 v227, v227
	v_rcp_f32_e32 v228, v228
	v_rcp_f32_e32 v229, v229
	v_rcp_f32_e32 v230, v230
	v_rcp_f32_e32 v231, v231
	v_rcp_f32_e32 v232, v232
	v_rcp_f32_e32 v233, v233
	v_mul_f32_e32 v226, v180, v226
	v_mul_f32_e32 v227, v181, v227
	v_mul_f32_e32 v228, v182, v228
	v_mul_f32_e32 v229, v183, v229
	v_mul_f32_e32 v230, v184, v230
	v_mul_f32_e32 v231, v185, v231
	v_mul_f32_e32 v232, v186, v232
	v_mul_f32_e32 v233, v187, v233
	v_cvt_pk_bf16_f32 v226, v226, v226
	v_cvt_pk_bf16_f32 v227, v227, v227
	v_cvt_pk_bf16_f32 v228, v228, v228
	v_cvt_pk_bf16_f32 v229, v229, v229
	v_cvt_pk_bf16_f32 v230, v230, v230
	v_cvt_pk_bf16_f32 v231, v231, v231
	v_cvt_pk_bf16_f32 v232, v232, v232
	v_cvt_pk_bf16_f32 v233, v233, v233
	global_store_short v204, v226, s[8:9]
	global_store_short v204, v227, s[8:9] offset:1024
	global_store_short v204, v228, s[8:9] offset:2048
	global_store_short v204, v229, s[8:9] offset:3072
	global_store_short v205, v230, s[8:9]
	global_store_short v205, v231, s[8:9] offset:-1024
	global_store_short v205, v232, s[8:9] offset:-2048
	global_store_short v205, v233, s[8:9] offset:-3072
	v_add_u32_e32 v204, 0x4000, v204
	v_add_u32_e32 v205, 0xffffc000, v205
	v_add_u32_e32 v206, 0xa000, v206
	v_add_u32_e32 v207, 0xffff6000, v207
	s_add_i32 s32, s32, 1
	s_sub_u32 s78, s78, 0x800
	s_subb_u32 s79, s79, 0

; __device__ __forceinline__ unsigned pk2(float lo, float hi) { const f32x2 v = {lo, hi}; return __builtin_bit_cast(unsigned, __builtin_convertvector(v, bf16x2_t)); }
; __device__ __forceinline__ float bflo(unsigned w) { return __uint_as_float(w << 16); }
; __device__ __forceinline__ float bfhi(unsigned w) { return __uint_as_float(w & 0xffff0000u); }
; #define LDS_FENCE() asm volatile("s_waitcnt lgkmcnt(0)" ::: "memory")
; template <bool BWD, int MODE  >
; __device__ __forceinline__ void ssm_pass(const bf16* proj, int rowbase, int g, const bf16x8* BBp, const bf16x8* CCp, float ar, float ai, float& sr, float& si,
;                                          LAS unsigned* XS, int lane, f32x4* ysc, const float* Dp, bf16* zbuf) {
;     ...
;     for (int c = 0; c < 16; ++c) {
;         const int ch = BWD ? 15 - c : c;
;         bf16x8 unext = ucur;
;         if (c < 15) unext = *(const bf16x8*)(up + (size_t)(BWD ? ch - 1 : ch + 1) * 32 * DIN);
;         f32x4 y0 = (f32x4){0.f, 0.f, 0.f, 0.f}, y1 = y0; bf16 uvl[8];
;         if (MODE == 2) {
;             y0 = ysc[(ch * 2 + 0) * 64 + lane]; y1 = ysc[(ch * 2 + 1) * 64 + lane];
; #pragma unroll
;             for (int q = 0; q < 8; ++q) uvl[q] = proj[(size_t)(rowbase + 32 * ch + 16 * (q >> 2) + 4 * (lane >> 4) + (q & 3)) * DIN + 768 + g * 16 + (lane & 15)];
;         }
;         f32x16 z16;
; #pragma unroll
;         for (int r = 0; r < 16; ++r) z16[r] = 0.f;
;         const f32x16 x0 = __builtin_amdgcn_mfma_f32_32x32x16_bf16(ucur, bb[0], z16, 0, 0, 0);
;         const f32x16 x1 = __builtin_amdgcn_mfma_f32_32x32x16_bf16(ucur, bb[1], z16, 0, 0, 0);
;         const f32x16 x2 = __builtin_amdgcn_mfma_f32_32x32x16_bf16(ucur, bb[2], z16, 0, 0, 0);
;         const f32x16 x3 = __builtin_amdgcn_mfma_f32_32x32x16_bf16(ucur, bb[3], z16, 0, 0, 0);
; #pragma unroll
;         for (int r = 0; r < 16; ++r) { const int t = crow(r, hi); XS[t * XS_STRIDE + ql] = pk2(x0[r], x2[r]); XS[t * XS_STRIDE + 32 + ql] = pk2(x1[r], x3[r]); }
;         LDS_FENCE();
; #pragma unroll
;         for (int tt = 0; tt < 32; ++tt) {
;             const int t = BWD ? 31 - tt : tt;
;             const unsigned v = XS[t * XS_STRIDE + lane];
;             const float nr = fmaf(ar, sr, fmaf(-ai, si, bflo(v))), ni = fmaf(ar, si, fmaf(ai, sr, bfhi(v)));
;             sr = nr; si = ni;
;             if (MODE > 0) XS[t * XS_STRIDE + lane] = pk2(sr, si);
.Lp3n_nopfb:
	global_load_dwordx4 v[188:191], v225, s[78:79] offset:1024 sc1
	global_load_dwordx4 v[192:195], v225, s[78:79] sc1
	global_load_ushort v196, v206, s[6:7]
	global_load_ushort v197, v206, s[6:7] offset:2560
	global_load_ushort v198, v206, s[80:81]
	global_load_ushort v199, v206, s[80:81] offset:2560
	global_load_ushort v200, v207, s[6:7]
	global_load_ushort v201, v207, s[6:7] offset:-2560
	global_load_ushort v202, v207, s[82:83]
	global_load_ushort v203, v207, s[82:83] offset:-2560
	v_mfma_f32_32x32x16_bf16 v[2:17], v[130:133], v[66:69], 0
	v_mfma_f32_32x32x16_bf16 v[18:33], v[130:133], v[70:73], 0
	v_mfma_f32_32x32x16_bf16 v[34:49], v[130:133], v[74:77], 0
	v_mfma_f32_32x32x16_bf16 v[50:65], v[130:133], v[78:81], 0
	v_mfma_f32_32x32x16_bf16 v[2:17], v[134:137], v[82:85], v[2:17]
	v_mfma_f32_32x32x16_bf16 v[18:33], v[134:137], v[86:89], v[18:33]
	v_mfma_f32_32x32x16_bf16 v[34:49], v[134:137], v[90:93], v[34:49]
	v_mfma_f32_32x32x16_bf16 v[50:65], v[134:137], v[94:97], v[50:65]
	s_nop 15
	s_nop 7
	v_fmac_f32_e32 v2, v150, v153
	v_fmac_f32_e32 v18, v151, v155
	v_fmac_f32_e32 v34, v147, v152
	v_fmac_f32_e32 v50, v149, v154
	v_fmac_f32_e32 v2, v146, v152
	v_fmac_f32_e32 v18, v148, v154
	v_fmac_f32_e32 v34, v146, v153
	v_fmac_f32_e32 v50, v148, v155
	v_fmac_f32_e32 v3, v150, v34
	v_fmac_f32_e32 v19, v151, v50
	v_fmac_f32_e32 v35, v147, v2
	v_fmac_f32_e32 v51, v149, v18
	v_fmac_f32_e32 v3, v146, v2
	v_fmac_f32_e32 v19, v148, v18
	v_fmac_f32_e32 v35, v146, v34
	v_fmac_f32_e32 v51, v148, v50
	v_fmac_f32_e32 v4, v150, v35
	v_fmac_f32_e32 v20, v151, v51
	v_fmac_f32_e32 v36, v147, v3
	v_fmac_f32_e32 v52, v149, v19
	v_fmac_f32_e32 v4, v146, v3
	v_fmac_f32_e32 v20, v148, v19
	v_fmac_f32_e32 v36, v146, v35
	v_fmac_f32_e32 v52, v148, v51
	v_fmac_f32_e32 v5, v150, v36
	v_fmac_f32_e32 v21, v151, v52
	v_fmac_f32_e32 v37, v147, v4
	v_fmac_f32_e32 v53, v149, v20
	v_fmac_f32_e32 v5, v146, v4
	v_fmac_f32_e32 v21, v148, v20
	v_fmac_f32_e32 v37, v146, v36
	v_fmac_f32_e32 v53, v148, v52
	v_fmac_f32_e32 v6, v150, v37
	v_fmac_f32_e32 v22, v151, v53
	v_fmac_f32_e32 v38, v147, v5
	v_fmac_f32_e32 v54, v149, v21
	v_fmac_f32_e32 v6, v146, v5
	v_fmac_f32_e32 v22, v148, v21
	v_fmac_f32_e32 v38, v146, v37
	v_fmac_f32_e32 v54, v148, v53
	v_fmac_f32_e32 v7, v150, v38
	v_fmac_f32_e32 v23, v151, v54
	v_fmac_f32_e32 v39, v147, v6
	v_fmac_f32_e32 v55, v149, v22
	v_fmac_f32_e32 v7, v146, v6
	v_fmac_f32_e32 v23, v148, v22
	v_fmac_f32_e32 v39, v146, v38
	v_fmac_f32_e32 v55, v148, v54
	v_fmac_f32_e32 v8, v150, v39
	v_fmac_f32_e32 v24, v151, v55
	v_fmac_f32_e32 v40, v147, v7
	v_fmac_f32_e32 v56, v149, v23
	v_fmac_f32_e32 v8, v146, v7
	v_fmac_f32_e32 v24, v148, v23
	v_fmac_f32_e32 v40, v146, v39
	v_fmac_f32_e32 v56, v148, v55
	v_fmac_f32_e32 v9, v150, v40
	v_fmac_f32_e32 v25, v151, v56
	v_fmac_f32_e32 v41, v147, v8
	v_fmac_f32_e32 v57, v149, v24
	v_fmac_f32_e32 v9, v146, v8
	v_fmac_f32_e32 v25, v148, v24
	v_fmac_f32_e32 v41, v146, v40
	v_fmac_f32_e32 v57, v148, v56
	v_fmac_f32_e32 v10, v150, v41
	v_fmac_f32_e32 v26, v151, v57
	v_fmac_f32_e32 v42, v147, v9
	v_fmac_f32_e32 v58, v149, v25
	v_fmac_f32_e32 v10, v146, v9
	v_fmac_f32_e32 v26, v148, v25
	v_fmac_f32_e32 v42, v146, v41
	v_fmac_f32_e32 v58, v148, v57
	v_fmac_f32_e32 v11, v150, v42
	v_fmac_f32_e32 v27, v151, v58
	v_fmac_f32_e32 v43, v147, v10
	v_fmac_f32_e32 v59, v149, v26
	v_fmac_f32_e32 v11, v146, v10
	v_fmac_f32_e32 v27, v148, v26
	v_fmac_f32_e32 v43, v146, v42
	v_fmac_f32_e32 v59, v148, v58
	v_fmac_f32_e32 v12, v150, v43
	v_fmac_f32_e32 v28, v151, v59
	v_fmac_f32_e32 v44, v147, v11
	v_fmac_f32_e32 v60, v149, v27
	v_fmac_f32_e32 v12, v146, v11
	v_fmac_f32_e32 v28, v148, v27
	v_fmac_f32_e32 v44, v146, v43
	v_fmac_f32_e32 v60, v148, v59
	v_fmac_f32_e32 v13, v150, v44
	v_fmac_f32_e32 v29, v151, v60
	v_fmac_f32_e32 v45, v147, v12
	v_fmac_f32_e32 v61, v149, v28
	v_fmac_f32_e32 v13, v146, v12
	v_fmac_f32_e32 v29, v148, v28
	v_fmac_f32_e32 v45, v146, v44
	v_fmac_f32_e32 v61, v148, v60
	v_fmac_f32_e32 v14, v150, v45
	v_fmac_f32_e32 v30, v151, v61
	v_fmac_f32_e32 v46, v147, v13
	v_fmac_f32_e32 v62, v149, v29
	v_fmac_f32_e32 v14, v146, v13
	v_fmac_f32_e32 v30, v148, v29
	v_fmac_f32_e32 v46, v146, v45
	v_fmac_f32_e32 v62, v148, v61
	v_fmac_f32_e32 v15, v150, v46
	v_fmac_f32_e32 v31, v151, v62
	v_fmac_f32_e32 v47, v147, v14
	v_fmac_f32_e32 v63, v149, v30
	v_fmac_f32_e32 v15, v146, v14
	v_fmac_f32_e32 v31, v148, v30
	v_fmac_f32_e32 v47, v146, v46
	v_fmac_f32_e32 v63, v148, v62
	v_fmac_f32_e32 v16, v150, v47
	v_fmac_f32_e32 v32, v151, v63
	v_fmac_f32_e32 v48, v147, v15
	v_fmac_f32_e32 v64, v149, v31
	v_fmac_f32_e32 v16, v146, v15
	v_fmac_f32_e32 v32, v148, v31
	v_fmac_f32_e32 v48, v146, v47
	v_fmac_f32_e32 v64, v148, v63
	v_fmac_f32_e32 v17, v150, v48
	v_fmac_f32_e32 v33, v151, v64
	v_fmac_f32_e32 v49, v147, v16
	v_fmac_f32_e32 v65, v149, v32
	v_fmac_f32_e32 v17, v146, v16
	v_fmac_f32_e32 v33, v148, v32
	v_fmac_f32_e32 v49, v146, v48
	v_fmac_f32_e32 v65, v148, v64
	v_cvt_pk_bf16_f32 v226, v2, v34
	v_cvt_pk_bf16_f32 v227, v18, v50
	v_cvt_pk_bf16_f32 v228, v3, v35
	v_cvt_pk_bf16_f32 v229, v19, v51
	v_cvt_pk_bf16_f32 v230, v4, v36
	v_cvt_pk_bf16_f32 v231, v20, v52
	v_cvt_pk_bf16_f32 v232, v5, v37
	v_cvt_pk_bf16_f32 v233, v21, v53
	v_cvt_pk_bf16_f32 v234, v6, v38
	v_cvt_pk_bf16_f32 v235, v22, v54
	v_cvt_pk_bf16_f32 v236, v7, v39
	v_cvt_pk_bf16_f32 v237, v23, v55
	v_cvt_pk_bf16_f32 v238, v8, v40
	v_cvt_pk_bf16_f32 v239, v24, v56
	v_cvt_pk_bf16_f32 v240, v9, v41
	v_cvt_pk_bf16_f32 v241, v25, v57
	v_cvt_pk_bf16_f32 v242, v10, v42
	v_cvt_pk_bf16_f32 v243, v26, v58
	v_cvt_pk_bf16_f32 v244, v11, v43
	v_cvt_pk_bf16_f32 v245, v27, v59
	v_cvt_pk_bf16_f32 v246, v12, v44
	v_cvt_pk_bf16_f32 v247, v28, v60
	v_cvt_pk_bf16_f32 v248, v13, v45
	v_cvt_pk_bf16_f32 v249, v29, v61
	v_cvt_pk_bf16_f32 v250, v14, v46
	v_cvt_pk_bf16_f32 v251, v30, v62
	v_cvt_pk_bf16_f32 v252, v15, v47
	v_cvt_pk_bf16_f32 v253, v31, v63
	v_cvt_pk_bf16_f32 v210, v16, v48
	v_cvt_pk_bf16_f32 v211, v32, v64
	v_cvt_pk_bf16_f32 v212, v17, v49
	v_cvt_pk_bf16_f32 v213, v33, v65
	ds_write2_b32 v158, v226, v227 offset0:0 offset1:32
	ds_write2_b32 v158, v228, v229 offset0:68 offset1:100
	ds_write2_b32 v158, v230, v231 offset0:136 offset1:168
	ds_write2_b32 v158, v232, v233 offset0:204 offset1:236
	ds_write2_b32 v159, v234, v235 offset0:0 offset1:32
	ds_write2_b32 v159, v236, v237 offset0:68 offset1:100
	ds_write2_b32 v159, v238, v239 offset0:136 offset1:168
	ds_write2_b32 v159, v240, v241 offset0:204 offset1:236
	ds_write2_b32 v160, v242, v243 offset0:0 offset1:32
	ds_write2_b32 v160, v244, v245 offset0:68 offset1:100
	ds_write2_b32 v160, v246, v247 offset0:136 offset1:168
	ds_write2_b32 v160, v248, v249 offset0:204 offset1:236
	ds_write2_b32 v161, v250, v251 offset0:0 offset1:32
	ds_write2_b32 v161, v252, v253 offset0:68 offset1:100
	ds_write2_b32 v161, v210, v211 offset0:136 offset1:168
	ds_write2_b32 v161, v212, v213 offset0:204 offset1:236
	v_mov_b32_e32 v152, v17
	v_mov_b32_e32 v153, v49
	v_mov_b32_e32 v154, v33
	v_mov_b32_e32 v155, v65
	s_waitcnt lgkmcnt(0)
; #define LAS __attribute__((address_space(3)))
; __device__ __forceinline__ unsigned f2bf(float f) { unsigned u = __builtin_bit_cast(unsigned, f); return (u + 0x7fffu + ((u >> 16) & 1u)) >> 16; }
; __device__ __forceinline__ float bf2f(bf16 v) { return __uint_as_float((unsigned)v << 16); }
; #define LDS_FENCE() asm volatile("s_waitcnt lgkmcnt(0)" ::: "memory")
; template <bool BWD, int MODE  >
; __device__ __forceinline__ void ssm_pass(const bf16* proj, int rowbase, int g, const bf16x8* BBp, const bf16x8* CCp, float ar, float ai, float& sr, float& si,
;                                          LAS unsigned* XS, int lane, f32x4* ysc, const float* Dp, bf16* zbuf) {
;     ...
;         if (MODE > 0) {
;             LDS_FENCE();
;             const LAS unsigned char* ab = (const LAS unsigned char*)XS + (lane & 15) * (XS_STRIDE * 4) + (lane >> 4) * 16;
; #pragma unroll
;             for (int kk = 0; kk < 4; ++kk) {
;                 const bf16x8 a0 = *(const LAS bf16x8*)(ab + kk * 64), a1 = *(const LAS bf16x8*)(ab + 16 * XS_STRIDE * 4 + kk * 64);
;                 y0 = __builtin_amdgcn_mfma_f32_16x16x32_bf16(a0, cc[kk], y0, 0, 0, 0);
;                 y1 = __builtin_amdgcn_mfma_f32_16x16x32_bf16(a1, cc[kk], y1, 0, 0, 0);
;             }
;             if (MODE == 1) { ysc[(ch * 2 + 0) * 64 + lane] = y0; ysc[(ch * 2 + 1) * 64 + lane] = y1; }
;             else {
;                 const int hcol = g * 16 + (lane & 15);
; #pragma unroll
;                 for (int rt = 0; rt < 2; ++rt)
; #pragma unroll
;                     for (int i = 0; i < 4; ++i) {
;                         const int row = rowbase + 32 * ch + 16 * rt + 4 * (lane >> 4) + i;
;                         const float uv = bf2f(uvl[rt * 4 + i]);
;                         const float y = (rt ? y1[i] : y0[i]) + dval * uv;
;                         const float zz = y * __builtin_amdgcn_rcpf(1.0f + __builtin_amdgcn_exp2f(-2.3022082f * (y + 0.044715f * y * y * y)));
;                         zbuf[(size_t)row * 512 + hcol] = (bf16)f2bf(zz);
;                     }
	ds_read_b128 v[226:229], v178 offset:0
	ds_read_b128 v[242:245], v178 offset:4352
	ds_read_b128 v[230:233], v178 offset:64
	ds_read_b128 v[246:249], v178 offset:4416
	ds_read_b128 v[234:237], v178 offset:128
	ds_read_b128 v[250:253], v178 offset:4480
	ds_read_b128 v[238:241], v178 offset:192
	ds_read_b128 v[210:213], v178 offset:4544
	s_waitcnt lgkmcnt(6)
	v_mfma_f32_16x16x32_bf16 v[180:183], v[226:229], v[98:101], 0
	v_mfma_f32_16x16x32_bf16 v[184:187], v[242:245], v[114:117], 0
	s_waitcnt lgkmcnt(4)
	v_mfma_f32_16x16x32_bf16 v[180:183], v[230:233], v[102:105], v[180:183]
	v_mfma_f32_16x16x32_bf16 v[184:187], v[246:249], v[118:121], v[184:187]
	s_waitcnt lgkmcnt(2)
	v_mfma_f32_16x16x32_bf16 v[180:183], v[234:237], v[106:109], v[180:183]
	v_mfma_f32_16x16x32_bf16 v[184:187], v[250:253], v[122:125], v[184:187]
	s_waitcnt lgkmcnt(0)
	v_mfma_f32_16x16x32_bf16 v[180:183], v[238:241], v[110:113], v[180:183]
	v_mfma_f32_16x16x32_bf16 v[184:187], v[210:213], v[126:129], v[184:187]
	s_waitcnt vmcnt(0)
	v_mov_b32_e32 v130, v138
	v_mov_b32_e32 v131, v139
	v_mov_b32_e32 v132, v140
	v_mov_b32_e32 v133, v141
	v_mov_b32_e32 v134, v142
	v_mov_b32_e32 v135, v143
	v_mov_b32_e32 v136, v144
	v_mov_b32_e32 v137, v145
	s_nop 7
	v_add_f32_e32 v180, v180, v191
	v_add_f32_e32 v181, v181, v190
	v_add_f32_e32 v182, v182, v189
	v_add_f32_e32 v183, v183, v188
	v_add_f32_e32 v184, v184, v195
	v_add_f32_e32 v185, v185, v194
	v_add_f32_e32 v186, v186, v193
	v_add_f32_e32 v187, v187, v192
	v_lshlrev_b32_e32 v196, 16, v196
	v_lshlrev_b32_e32 v197, 16, v197
	v_lshlrev_b32_e32 v198, 16, v198
	v_lshlrev_b32_e32 v199, 16, v199
	v_lshlrev_b32_e32 v200, 16, v200
	v_lshlrev_b32_e32 v201, 16, v201
	v_lshlrev_b32_e32 v202, 16, v202
	v_lshlrev_b32_e32 v203, 16, v203
	v_fmac_f32_e32 v180, v208, v196
	v_fmac_f32_e32 v181, v208, v197
	v_fmac_f32_e32 v182, v208, v198
	v_fmac_f32_e32 v183, v208, v199
	v_fmac_f32_e32 v184, v208, v200
	v_fmac_f32_e32 v185, v208, v201
	v_fmac_f32_e32 v186, v208, v202
	v_fmac_f32_e32 v187, v208, v203
	v_mul_f32_e32 v226, 0x3d372713, v180
	v_mul_f32_e32 v227, 0x3d372713, v181
	v_mul_f32_e32 v228, 0x3d372713, v182
	v_mul_f32_e32 v229, 0x3d372713, v183
	v_mul_f32_e32 v230, 0x3d372713, v184
	v_mul_f32_e32 v231, 0x3d372713, v185
	v_mul_f32_e32 v232, 0x3d372713, v186
	v_mul_f32_e32 v233, 0x3d372713, v187
	v_mul_f32_e32 v226, v180, v226
	v_mul_f32_e32 v227, v181, v227
	v_mul_f32_e32 v228, v182, v228
	v_mul_f32_e32 v229, v183, v229
	v_mul_f32_e32 v230, v184, v230
	v_mul_f32_e32 v231, v185, v231
	v_mul_f32_e32 v232, v186, v232
	v_mul_f32_e32 v233, v187, v233
	v_fma_f32 v226, v180, v226, v180
	v_fma_f32 v227, v181, v227, v181
	v_fma_f32 v228, v182, v228, v182
	v_fma_f32 v229, v183, v229, v183
	v_fma_f32 v230, v184, v230, v184
	v_fma_f32 v231, v185, v231, v185
	v_fma_f32 v232, v186, v232, v186
	v_fma_f32 v233, v187, v233, v187
	v_mul_f32_e32 v226, 0xc0135761, v226
	v_mul_f32_e32 v227, 0xc0135761, v227
	v_mul_f32_e32 v228, 0xc0135761, v228
	v_mul_f32_e32 v229, 0xc0135761, v229
	v_mul_f32_e32 v230, 0xc0135761, v230
	v_mul_f32_e32 v231, 0xc0135761, v231
	v_mul_f32_e32 v232, 0xc0135761, v232
	v_mul_f32_e32 v233, 0xc0135761, v233
	v_exp_f32_e32 v226, v226
	v_exp_f32_e32 v227, v227
	v_exp_f32_e32 v228, v228
	v_exp_f32_e32 v229, v229
	v_exp_f32_e32 v230, v230
	v_exp_f32_e32 v231, v231
	v_exp_f32_e32 v232, v232
	v_exp_f32_e32 v233, v233
	v_add_f32_e32 v226, 1.0, v226
	v_add_f32_e32 v227, 1.0, v227
	v_add_f32_e32 v228, 1.0, v228
	v_add_f32_e32 v229, 1.0, v229
	v_add_f32_e32 v230, 1.0, v230
	v_add_f32_e32 v231, 1.0, v231
	v_add_f32_e32 v232, 1.0, v232
	v_add_f32_e32 v233, 1.0, v233
	v_rcp_f32_e32 v226, v226
	v_rcp_f32_e32 v227, v227
	v_rcp_f32_e32 v228, v228
	v_rcp_f32_e32 v229, v229
	v_rcp_f32_e32 v230, v230
	v_rcp_f32_e32 v231, v231
	v_rcp_f32_e32 v232, v232
	v_rcp_f32_e32 v233, v233
	v_mul_f32_e32 v226, v180, v226
	v_mul_f32_e32 v227, v181, v227
	v_mul_f32_e32 v228, v182, v228
	v_mul_f32_e32 v229, v183, v229
	v_mul_f32_e32 v230, v184, v230
	v_mul_f32_e32 v231, v185, v231
	v_mul_f32_e32 v232, v186, v232
	v_mul_f32_e32 v233, v187, v233
	v_cvt_pk_bf16_f32 v226, v226, v226
	v_cvt_pk_bf16_f32 v227, v227, v227
	v_cvt_pk_bf16_f32 v228, v228, v228
	v_cvt_pk_bf16_f32 v229, v229, v229
	v_cvt_pk_bf16_f32 v230, v230, v230
	v_cvt_pk_bf16_f32 v231, v231, v231
	v_cvt_pk_bf16_f32 v232, v232, v232
	v_cvt_pk_bf16_f32 v233, v233, v233
	global_store_short v204, v226, s[8:9]
	global_store_short v204, v227, s[8:9] offset:1024
	global_store_short v204, v228, s[8:9] offset:2048
	global_store_short v204, v229, s[8:9] offset:3072
	global_store_short v205, v230, s[8:9]
	global_store_short v205, v231, s[8:9] offset:-1024
	global_store_short v205, v232, s[8:9] offset:-2048
	global_store_short v205, v233, s[8:9] offset:-3072
	v_add_u32_e32 v204, 0x4000, v204
	v_add_u32_e32 v205, 0xffffc000, v205
	v_add_u32_e32 v206, 0xa000, v206
	v_add_u32_e32 v207, 0xffff6000, v207
	s_sub_u32 s78, s78, 0x800
	s_subb_u32 s79, s79, 0
	s_add_i32 s32, s32, 1
	s_cmp_lt_u32 s32, 8
	s_cbranch_scc1 .Lp3n_loopb
	v_add_u32_e32 v204, 0x10000, v204
	v_add_u32_e32 v205, 0x30000, v205
	v_add_u32_e32 v206, 0x28000, v206
	v_add_u32_e32 v207, 0x78000, v207
	s_add_i32 s45, s45, 1
	s_cmp_lt_u32 s45, 4
	s_cbranch_scc1 .Lp3n_block
	s_add_i32 s58, s58, s20
	s_cmpk_gt_i32 s58, 0xff
	s_cbranch_scc0 .Lp3n_task
